# attention first half-step: first eight P.V V-fragment LDS reads issued right after the last QK MFMA so their latency overlaps the bf16 pack and permlane tail
# speedup vs baseline: 1.0039x; 1.0039x over previous
; #define SBAR() __builtin_amdgcn_sched_barrier(0)
; #define SLOAD(i, k0) do { sr_[i].vs0 = *reinterpret_cast<const bf16x8*>(&Vh[(size_t)((k0) + sr) * 128 + sc]); sr_[i].vs1 = *reinterpret_cast<const bf16x8*>(&Vh[(size_t)((k0) + 32 + sr) * 128 + sc]); \
;     sr_[i].ks0 = *reinterpret_cast<const bf16x8*>(&Kh[(size_t)((k0) + kr) * 64 + kc]); } while (0)
; DEV void finishSM(f32x16& p0, f32x16& p1, float alpha, float& l_reg, bf16x8& pa0, bf16x8& pa1, bf16x8& pa2, bf16x8& pa3) {
; #pragma unroll
;   for (int r = 0; r < 16; ++r) p1[r] = __builtin_amdgcn_exp2f(p1[r]);
;   float ps = 0;
; #pragma unroll
;   for (int r = 0; r < 16; ++r) ps += p0[r];
; #pragma unroll
;   for (int r = 0; r < 16; ++r) ps += p1[r];
;   { auto rr = __builtin_amdgcn_permlane32_swap(__float_as_uint(ps), __float_as_uint(ps), false, false);
;     ps = __uint_as_float(rr[0]) + __uint_as_float(rr[1]); }
;   l_reg = l_reg * alpha + ps;
;     ...
;   PK4(p0, 0, pa0); PK4(p0, 8, pa1); PK4(p1, 0, pa2); PK4(p1, 8, pa3);
; DEV void attn_pass(const u16* __restrict__ Qb, const u16* __restrict__ Kh, const u16* __restrict__ Vh, int seq, f32x16* o, float* rli) {
;     ...
;     SBAR(); qkt(pB0, pB1, K_lds + b0 * AT_SHM_K, qr, r32, hi);
;     finishSM(pA0, pA1, alA, l_reg, pa0, pa1, pa2, pa3); SBAR();
;     SLOAD(SO, (j + 2) * 64); SBAR();
;     pv_d0(o, vb0 + bm1 * AT_SHM_V, pa0, pa1, pa2, pa3); partialSM(pB0, pB1, m_reg, mnB, alB);
.LBB0_70:
	s_mul_hi_u32 s1, s9, 0xaaaaaaab
	s_lshr_b32 s1, s1, 1
	s_mul_i32 s1, s1, 0xc000
	v_subrev_u32_e32 v190, s1, v184
	s_mul_hi_u32 s1, s51, 0xaaaaaaab
	s_mul_hi_u32 s0, s66, 0xaaaaaaab
	s_lshr_b32 s12, s1, 1
	s_lshr_b32 s0, s0, 1
	s_mul_i32 s1, s12, 0x6000
	s_mul_i32 s15, s0, 0x6000
	v_subrev_u32_e32 v64, s1, v198
	s_mul_i32 s0, s0, 0xc000
	v_subrev_u32_e32 v216, s15, v180
	v_subrev_u32_e32 v164, s1, v200
	v_subrev_u32_e32 v217, s0, v203
	v_subrev_u32_e32 v218, s0, v204
	v_subrev_u32_e32 v191, s1, v209
	v_subrev_u32_e32 v192, s1, v210
	v_add_u32_e32 v141, s14, v181
	v_add_u32_e32 v68, v141, v64
	ds_read_b128 v[64:67], v68
	ds_read_b128 v[68:71], v68 offset:4096
	v_add_u32_e32 v186, v141, v164
	ds_read_b128 v[164:167], v186
	ds_read_b128 v[186:189], v186 offset:4096
	s_waitcnt vmcnt(0)
	v_add_u32_e32 v72, s8, v202
	v_add_u32_e32 v73, v72, v218
	ds_write_b128 v73, v[116:119]
	v_add_u32_e32 v73, v72, v217
	s_add_i32 s13, s14, 0
	ds_write_b128 v73, v[112:115]
	v_add_u32_e32 v73, s13, v216
	ds_write_b128 v73, v[120:123]
	v_exp_f32_e32 v134, v134
	s_waitcnt lgkmcnt(6)
	v_mfma_f32_32x32x16_bf16 v[80:95], v[64:67], v[108:111], v[236:251]
	v_exp_f32_e32 v135, v135
	v_exp_f32_e32 v132, v132
	v_exp_f32_e32 v133, v133
	v_exp_f32_e32 v130, v130
	v_exp_f32_e32 v131, v131
	v_exp_f32_e32 v128, v128
	v_exp_f32_e32 v129, v129
	s_waitcnt lgkmcnt(5)
	v_mfma_f32_32x32x16_bf16 v[64:79], v[68:71], v[108:111], v[236:251]
	v_exp_f32_e32 v126, v126
	v_exp_f32_e32 v127, v127
	v_exp_f32_e32 v124, v124
	v_exp_f32_e32 v125, v125
	s_waitcnt lgkmcnt(4)
	v_mfma_f32_32x32x16_bf16 v[80:95], v[164:167], v[104:107], v[80:95]
	s_waitcnt lgkmcnt(3)
	v_mfma_f32_32x32x16_bf16 v[64:79], v[186:189], v[104:107], v[64:79]
	v_add_u32_e32 v186, v141, v191
	ds_read_b128 v[164:167], v186
	ds_read_b128 v[186:189], v186 offset:4096
	s_waitcnt lgkmcnt(1)
	v_mfma_f32_32x32x16_bf16 v[80:95], v[164:167], v[100:103], v[80:95]
	s_waitcnt lgkmcnt(0)
	v_mfma_f32_32x32x16_bf16 v[64:79], v[186:189], v[100:103], v[64:79]
	v_add_u32_e32 v186, v141, v192
	ds_read_b128 v[164:167], v186
	ds_read_b128 v[186:189], v186 offset:4096
	s_waitcnt lgkmcnt(1)
	v_mfma_f32_32x32x16_bf16 v[80:95], v[164:167], v[96:99], v[80:95]
	v_exp_f32_e32 v166, v136
	v_add_f32_e32 v136, v160, v150
	v_add_f32_e32 v136, v151, v136
	v_add_f32_e32 v136, v161, v136
	v_add_f32_e32 v136, v158, v136
	v_add_f32_e32 v136, v214, v136
	v_add_f32_e32 v136, v159, v136
	v_add_f32_e32 v136, v215, v136
	v_add_f32_e32 v136, v142, v136
	v_add_f32_e32 v136, v146, v136
	v_add_f32_e32 v136, v143, v136
	v_add_f32_e32 v136, v147, v136
	v_exp_f32_e32 v164, v138
	v_add_f32_e32 v136, v144, v136
	v_exp_f32_e32 v165, v139
	v_add_f32_e32 v136, v148, v136
	v_add_f32_e32 v136, v145, v136
	v_exp_f32_e32 v167, v137
	v_add_f32_e32 v136, v149, v136
	v_add_f32_e32 v136, v164, v136
	v_add_f32_e32 v136, v165, v136
	v_add_f32_e32 v136, v166, v136
	v_add_f32_e32 v136, v167, v136
	v_add_f32_e32 v136, v134, v136
	v_add_f32_e32 v136, v135, v136
	v_add_f32_e32 v136, v132, v136
	v_add_f32_e32 v136, v133, v136
	v_add_f32_e32 v136, v130, v136
	v_add_f32_e32 v136, v131, v136
	s_waitcnt lgkmcnt(0)
	v_mfma_f32_32x32x16_bf16 v[64:79], v[186:189], v[96:99], v[64:79]
	v_add_u32_e32 v216, s8, v190
	ds_read_b64_tr_b16 v[186:187], v216 offset:0
	ds_read_b64_tr_b16 v[188:189], v216 offset:0x800
	ds_read_b64_tr_b16 v[190:191], v216 offset:0x1000
	ds_read_b64_tr_b16 v[192:193], v216 offset:0x1800
	ds_read_b64_tr_b16 v[220:221], v216 offset:0x2000
	ds_read_b64_tr_b16 v[222:223], v216 offset:0x2800
	ds_read_b64_tr_b16 v[224:225], v216 offset:0x3000
	ds_read_b64_tr_b16 v[226:227], v216 offset:0x3800
	v_add_f32_e32 v136, v128, v136
	v_add_f32_e32 v136, v129, v136
	v_add_f32_e32 v136, v126, v136
	v_add_f32_e32 v136, v127, v136
	v_add_f32_e32 v136, v124, v136
	v_add_f32_e32 v211, v125, v136
	v_mov_b32_e32 v212, v211
	v_cvt_pk_bf16_f32 v136, v150, v160
	v_cvt_pk_bf16_f32 v138, v158, v214
	s_nop 1
	v_permlane32_swap_b32_e32 v211, v212
	v_cvt_pk_bf16_f32 v137, v151, v161
	v_cvt_pk_bf16_f32 v139, v159, v215
	v_permlane32_swap_b32_e32 v136, v138
	v_cvt_pk_bf16_f32 v142, v142, v146
	v_cvt_pk_bf16_f32 v143, v143, v147
	v_cvt_pk_bf16_f32 v144, v144, v148
	v_cvt_pk_bf16_f32 v145, v145, v149
	v_cvt_pk_bf16_f32 v146, v164, v165
	v_cvt_pk_bf16_f32 v147, v166, v167
	v_cvt_pk_bf16_f32 v148, v134, v135
	v_cvt_pk_bf16_f32 v149, v132, v133
	v_cvt_pk_bf16_f32 v164, v130, v131
	v_cvt_pk_bf16_f32 v165, v128, v129
	v_cvt_pk_bf16_f32 v166, v126, v127
	v_cvt_pk_bf16_f32 v167, v124, v125
	v_permlane32_swap_b32_e32 v137, v139
	v_permlane32_swap_b32_e32 v142, v144
	v_permlane32_swap_b32_e32 v143, v145
	v_permlane32_swap_b32_e32 v146, v148
	v_permlane32_swap_b32_e32 v147, v149
	v_permlane32_swap_b32_e32 v164, v166
	v_permlane32_swap_b32_e32 v165, v167
	v_lshl_add_u64 v[158:159], v[156:157], 0, s[82:83]
	v_add_co_u32_e32 v124, vcc, s94, v158
	v_lshl_add_u64 v[160:161], v[154:155], 0, s[82:83]
	s_nop 0
	v_addc_co_u32_e32 v125, vcc, 0, v159, vcc
	v_add_co_u32_e32 v128, vcc, s95, v158
	s_mov_b32 s0, 0x18606000
	s_nop 0
	v_addc_co_u32_e32 v129, vcc, 0, v159, vcc
	v_add_co_u32_e32 v132, vcc, s0, v160
	global_load_dwordx4 v[124:127], v[124:125], off
	s_nop 0
	global_load_dwordx4 v[128:131], v[128:129], off
	v_addc_co_u32_e32 v133, vcc, 0, v161, vcc
	global_load_dwordx4 v[132:135], v[132:133], off
	s_waitcnt lgkmcnt(0)
; #define SBAR() __builtin_amdgcn_sched_barrier(0)
; DEV void partialSM(f32x16& p0, f32x16& p1, float& m_reg, float& mn, float& alpha) {
;   constexpr float C = AT_SCALE * 1.4426950408889634f;
;   float pmax = p0[0];
; #pragma unroll
;   for (int r = 1; r < 16; ++r) pmax = fmaxf(pmax, p0[r]);
; #pragma unroll
;   for (int r = 0; r < 16; ++r) pmax = fmaxf(pmax, p1[r]);
;   { auto rr = __builtin_amdgcn_permlane32_swap(__float_as_uint(pmax), __float_as_uint(pmax), false, false);
;     pmax = fmaxf(__uint_as_float(rr[0]), __uint_as_float(rr[1])); }
;   if (__builtin_expect(__all(pmax - m_reg <= AT_THR / AT_SCALE), 1)) { mn = m_reg; alpha = 1.f; }
;   else { mn = fmaxf(m_reg, pmax); alpha = __builtin_amdgcn_exp2f((m_reg - mn) * C); m_reg = mn; }
; template <int D0> DEV void pv_one(f32x16& od, int vb, bf16x8 pa0, bf16x8 pa1, bf16x8 pa2, bf16x8 pa3) {
;   const s16x4 l0 = tr_read<v_rd_off(D0, 0, 0)>(vb), h0 = tr_read<v_rd_off(D0, 0, 1)>(vb), l1 = tr_read<v_rd_off(D0, 1, 0)>(vb), h1 = tr_read<v_rd_off(D0, 1, 1)>(vb);
;   const s16x4 l2 = tr_read<v_rd_off(D0, 2, 0)>(vb), h2 = tr_read<v_rd_off(D0, 2, 1)>(vb), l3 = tr_read<v_rd_off(D0, 3, 0)>(vb), h3 = tr_read<v_rd_off(D0, 3, 1)>(vb);
;   asm volatile("s_waitcnt lgkmcnt(0)" ::: "memory"); SBAR();
;     ...
;   od = __builtin_amdgcn_mfma_f32_32x32x16_bf16(pa0, PK(l0, h0), od, 0, 0, 0);
;   od = __builtin_amdgcn_mfma_f32_32x32x16_bf16(pa1, PK(l1, h1), od, 0, 0, 0);
;   od = __builtin_amdgcn_mfma_f32_32x32x16_bf16(pa2, PK(l2, h2), od, 0, 0, 0);
;   od = __builtin_amdgcn_mfma_f32_32x32x16_bf16(pa3, PK(l3, h3), od, 0, 0, 0);
;     ...
; }
; DEV void pv_d0(f32x16* o, int vb, bf16x8 pa0, bf16x8 pa1, bf16x8 pa2, bf16x8 pa3) {
;   pv_one<0>(o[0], vb, pa0, pa1, pa2, pa3); pv_one<1>(o[1], vb, pa0, pa1, pa2, pa3); pv_one<2>(o[2], vb, pa0, pa1, pa2, pa3); pv_one<3>(o[3], vb, pa0, pa1, pa2, pa3);
	s_nop 0
	v_mfma_f32_32x32x16_bf16 v[0:15], v[136:139], v[186:189], v[0:15]
	ds_read_b64_tr_b16 v[186:187], v216 offset:0x200
	ds_read_b64_tr_b16 v[188:189], v216 offset:0xa00
	v_mfma_f32_32x32x16_bf16 v[0:15], v[142:145], v[190:193], v[0:15]
	ds_read_b64_tr_b16 v[190:191], v216 offset:0x1200
	ds_read_b64_tr_b16 v[192:193], v216 offset:0x1a00
	v_mfma_f32_32x32x16_bf16 v[0:15], v[146:149], v[220:223], v[0:15]
	ds_read_b64_tr_b16 v[220:221], v216 offset:0x2200
	ds_read_b64_tr_b16 v[222:223], v216 offset:0x2a00
	v_mfma_f32_32x32x16_bf16 v[0:15], v[164:167], v[224:227], v[0:15]
	ds_read_b64_tr_b16 v[224:225], v216 offset:0x3200
	ds_read_b64_tr_b16 v[226:227], v216 offset:0x3a00
	s_waitcnt lgkmcnt(0)
	v_mfma_f32_32x32x16_bf16 v[48:63], v[136:139], v[186:189], v[48:63]
	ds_read_b64_tr_b16 v[186:187], v216 offset:0x400
	ds_read_b64_tr_b16 v[188:189], v216 offset:0xc00
	v_mfma_f32_32x32x16_bf16 v[48:63], v[142:145], v[190:193], v[48:63]
	ds_read_b64_tr_b16 v[190:191], v216 offset:0x1400
	ds_read_b64_tr_b16 v[192:193], v216 offset:0x1c00
	v_mfma_f32_32x32x16_bf16 v[48:63], v[146:149], v[220:223], v[48:63]
	ds_read_b64_tr_b16 v[220:221], v216 offset:0x2400
	ds_read_b64_tr_b16 v[222:223], v216 offset:0x2c00
	v_mfma_f32_32x32x16_bf16 v[48:63], v[164:167], v[224:227], v[48:63]
	ds_read_b64_tr_b16 v[224:225], v216 offset:0x3400
	ds_read_b64_tr_b16 v[226:227], v216 offset:0x3c00
	s_waitcnt lgkmcnt(0)
	v_mfma_f32_32x32x16_bf16 v[32:47], v[136:139], v[186:189], v[32:47]
	ds_read_b64_tr_b16 v[186:187], v216 offset:0x600
	ds_read_b64_tr_b16 v[188:189], v216 offset:0xe00
	v_mfma_f32_32x32x16_bf16 v[32:47], v[142:145], v[190:193], v[32:47]
	ds_read_b64_tr_b16 v[190:191], v216 offset:0x1600
	ds_read_b64_tr_b16 v[192:193], v216 offset:0x1e00
	v_mfma_f32_32x32x16_bf16 v[32:47], v[146:149], v[220:223], v[32:47]
	ds_read_b64_tr_b16 v[220:221], v216 offset:0x2600
	ds_read_b64_tr_b16 v[222:223], v216 offset:0x2e00
	v_mfma_f32_32x32x16_bf16 v[32:47], v[164:167], v[224:227], v[32:47]
	ds_read_b64_tr_b16 v[224:225], v216 offset:0x3600
	ds_read_b64_tr_b16 v[226:227], v216 offset:0x3e00
	s_waitcnt lgkmcnt(0)
	v_mfma_f32_32x32x16_bf16 v[16:31], v[136:139], v[186:189], v[16:31]
	v_max_f32_e32 v136, v80, v81
	v_max3_f32 v136, v136, v82, v83
	v_max3_f32 v136, v136, v84, v85
	v_max3_f32 v136, v136, v86, v87
	v_max3_f32 v136, v136, v88, v89
	v_max3_f32 v136, v136, v90, v91
	v_max3_f32 v136, v136, v92, v93
	v_max3_f32 v136, v136, v94, v95
	v_mfma_f32_32x32x16_bf16 v[16:31], v[142:145], v[190:193], v[16:31]
	v_max3_f32 v136, v136, v64, v65
	v_max3_f32 v136, v136, v66, v67
	v_max3_f32 v136, v136, v68, v69
	v_max3_f32 v136, v136, v70, v71
	v_max3_f32 v136, v136, v72, v73
	v_max3_f32 v136, v136, v74, v75
	v_max3_f32 v136, v136, v76, v77
	v_max3_f32 v136, v136, v78, v79
	v_mfma_f32_32x32x16_bf16 v[16:31], v[146:149], v[220:223], v[16:31]
	v_mov_b32_e32 v137, v136
	s_nop 1
	v_permlane32_swap_b32_e32 v136, v137
	v_max_f32_e32 v136, v136, v137
	v_cmp_ge_f32_e32 vcc, s18, v136
	v_mfma_f32_32x32x16_bf16 v[16:31], v[164:167], v[224:227], v[16:31]
	s_cmp_eq_u64 vcc, exec
	s_cselect_b64 s[0:1], -1, 0
	s_cbranch_scc1 .Lattn_fast1
	v_max_f32_e32 v136, 0, v136
	v_exp_f32_e64 v137, -v136

; #define SBAR() __builtin_amdgcn_sched_barrier(0)
; #define SLOAD(i, k0) do { sr_[i].vs0 = *reinterpret_cast<const bf16x8*>(&Vh[(size_t)((k0) + sr) * 128 + sc]); sr_[i].vs1 = *reinterpret_cast<const bf16x8*>(&Vh[(size_t)((k0) + 32 + sr) * 128 + sc]); \
;     sr_[i].ks0 = *reinterpret_cast<const bf16x8*>(&Kh[(size_t)((k0) + kr) * 64 + kc]); } while (0)
; DEV void finishSM(f32x16& p0, f32x16& p1, float alpha, float& l_reg, bf16x8& pa0, bf16x8& pa1, bf16x8& pa2, bf16x8& pa3) {
; #pragma unroll
;   for (int r = 0; r < 16; ++r) p1[r] = __builtin_amdgcn_exp2f(p1[r]);
;   float ps = 0;
; #pragma unroll
;   for (int r = 0; r < 16; ++r) ps += p0[r];
; #pragma unroll
;   for (int r = 0; r < 16; ++r) ps += p1[r];
;   { auto rr = __builtin_amdgcn_permlane32_swap(__float_as_uint(ps), __float_as_uint(ps), false, false);
;     ps = __uint_as_float(rr[0]) + __uint_as_float(rr[1]); }
;   l_reg = l_reg * alpha + ps;
;     ...
;   PK4(p0, 0, pa0); PK4(p0, 8, pa1); PK4(p1, 0, pa2); PK4(p1, 8, pa3);
; DEV void attn_pass(const u16* __restrict__ Qb, const u16* __restrict__ Kh, const u16* __restrict__ Vh, int seq, f32x16* o, float* rli) {
;     ...
;     SBAR(); qkt(pB0, pB1, K_lds + b0 * AT_SHM_K, qr, r32, hi);
;     finishSM(pA0, pA1, alA, l_reg, pa0, pa1, pa2, pa3); SBAR();
;     SLOAD(SO, (j + 2) * 64); SBAR();
;     pv_d0(o, vb0 + bm1 * AT_SHM_V, pa0, pa1, pa2, pa3); partialSM(pB0, pB1, m_reg, mnB, alB);
.LBB0_90:
	s_mul_hi_u32 s1, s9, 0xaaaaaaab
	s_lshr_b32 s1, s1, 1
	s_mul_i32 s1, s1, 0xc000
	v_subrev_u32_e32 v190, s1, v199
	s_mul_hi_u32 s1, s47, 0xaaaaaaab
	s_mul_hi_u32 s0, s46, 0xaaaaaaab
	s_lshr_b32 s12, s1, 1
	s_lshr_b32 s0, s0, 1
	s_mul_i32 s1, s12, 0x6000
	s_mul_i32 s15, s0, 0x6000
	v_subrev_u32_e32 v64, s1, v201
	s_mul_i32 s0, s0, 0xc000
	v_subrev_u32_e32 v219, s15, v183
	v_subrev_u32_e32 v164, s1, v203
	v_subrev_u32_e32 v220, s0, v206
	v_subrev_u32_e32 v221, s0, v207
	v_subrev_u32_e32 v191, s1, v212
	v_subrev_u32_e32 v192, s1, v213
	v_add_u32_e32 v141, s14, v184
	v_add_u32_e32 v68, v141, v64
	ds_read_b128 v[64:67], v68
	ds_read_b128 v[68:71], v68 offset:4096
	v_add_u32_e32 v186, v141, v164
	ds_read_b128 v[164:167], v186
	ds_read_b128 v[186:189], v186 offset:4096
	s_waitcnt vmcnt(0)
	v_add_u32_e32 v72, s8, v205
	v_add_u32_e32 v73, v72, v221
	ds_write_b128 v73, v[116:119]
	v_add_u32_e32 v73, v72, v220
	s_add_i32 s13, s14, 0
	ds_write_b128 v73, v[112:115]
	v_add_u32_e32 v73, s13, v219
	ds_write_b128 v73, v[120:123]
	v_exp_f32_e32 v134, v134
	s_waitcnt lgkmcnt(6)
	v_mfma_f32_32x32x16_bf16 v[80:95], v[64:67], v[108:111], v[236:251]
	v_exp_f32_e32 v135, v135
	v_exp_f32_e32 v132, v132
	v_exp_f32_e32 v133, v133
	v_exp_f32_e32 v130, v130
	v_exp_f32_e32 v131, v131
	v_exp_f32_e32 v128, v128
	v_exp_f32_e32 v129, v129
	s_waitcnt lgkmcnt(5)
	v_mfma_f32_32x32x16_bf16 v[64:79], v[68:71], v[108:111], v[236:251]
	v_exp_f32_e32 v126, v126
	v_exp_f32_e32 v127, v127
	v_exp_f32_e32 v124, v124
	v_exp_f32_e32 v125, v125
	s_waitcnt lgkmcnt(4)
	v_mfma_f32_32x32x16_bf16 v[80:95], v[164:167], v[104:107], v[80:95]
	s_waitcnt lgkmcnt(3)
	v_mfma_f32_32x32x16_bf16 v[64:79], v[186:189], v[104:107], v[64:79]
	v_add_u32_e32 v186, v141, v191
	ds_read_b128 v[164:167], v186
	ds_read_b128 v[186:189], v186 offset:4096
	s_waitcnt lgkmcnt(1)
	v_mfma_f32_32x32x16_bf16 v[80:95], v[164:167], v[100:103], v[80:95]
	s_waitcnt lgkmcnt(0)
	v_mfma_f32_32x32x16_bf16 v[64:79], v[186:189], v[100:103], v[64:79]
	v_add_u32_e32 v186, v141, v192
	ds_read_b128 v[164:167], v186
	ds_read_b128 v[186:189], v186 offset:4096
	s_waitcnt lgkmcnt(1)
	v_mfma_f32_32x32x16_bf16 v[80:95], v[164:167], v[96:99], v[80:95]
	v_exp_f32_e32 v166, v136
	v_add_f32_e32 v136, v170, v150
	v_add_f32_e32 v136, v151, v136
	v_add_f32_e32 v136, v171, v136
	v_add_f32_e32 v136, v168, v136
	v_add_f32_e32 v136, v217, v136
	v_add_f32_e32 v136, v169, v136
	v_add_f32_e32 v136, v218, v136
	v_add_f32_e32 v136, v142, v136
	v_add_f32_e32 v136, v146, v136
	v_add_f32_e32 v136, v143, v136
	v_add_f32_e32 v136, v147, v136
	v_exp_f32_e32 v164, v138
	v_add_f32_e32 v136, v144, v136
	v_exp_f32_e32 v165, v139
	v_add_f32_e32 v136, v148, v136
	v_add_f32_e32 v136, v145, v136
	v_exp_f32_e32 v167, v137
	v_add_f32_e32 v136, v149, v136
	v_add_f32_e32 v136, v164, v136
	v_add_f32_e32 v136, v165, v136
	v_add_f32_e32 v136, v166, v136
	v_add_f32_e32 v136, v167, v136
	v_add_f32_e32 v136, v134, v136
	v_add_f32_e32 v136, v135, v136
	v_add_f32_e32 v136, v132, v136
	v_add_f32_e32 v136, v133, v136
	v_add_f32_e32 v136, v130, v136
	v_add_f32_e32 v136, v131, v136
	s_waitcnt lgkmcnt(0)
	v_mfma_f32_32x32x16_bf16 v[64:79], v[186:189], v[96:99], v[64:79]
	v_add_u32_e32 v219, s8, v190
	ds_read_b64_tr_b16 v[186:187], v219 offset:0
	ds_read_b64_tr_b16 v[188:189], v219 offset:0x800
	ds_read_b64_tr_b16 v[190:191], v219 offset:0x1000
	ds_read_b64_tr_b16 v[192:193], v219 offset:0x1800
	ds_read_b64_tr_b16 v[222:223], v219 offset:0x2000
	ds_read_b64_tr_b16 v[224:225], v219 offset:0x2800
	ds_read_b64_tr_b16 v[226:227], v219 offset:0x3000
	ds_read_b64_tr_b16 v[228:229], v219 offset:0x3800
	v_add_f32_e32 v136, v128, v136
	v_add_f32_e32 v136, v129, v136
	v_add_f32_e32 v136, v126, v136
	v_add_f32_e32 v136, v127, v136
	v_add_f32_e32 v136, v124, v136
	v_add_f32_e32 v214, v125, v136
	v_mov_b32_e32 v215, v214
	v_cvt_pk_bf16_f32 v136, v150, v170
	v_cvt_pk_bf16_f32 v138, v168, v217
	s_nop 1
	v_permlane32_swap_b32_e32 v214, v215
	v_cvt_pk_bf16_f32 v137, v151, v171
	v_cvt_pk_bf16_f32 v139, v169, v218
	v_permlane32_swap_b32_e32 v136, v138
	v_cvt_pk_bf16_f32 v142, v142, v146
	v_cvt_pk_bf16_f32 v143, v143, v147
	v_cvt_pk_bf16_f32 v144, v144, v148
	v_cvt_pk_bf16_f32 v145, v145, v149
	v_cvt_pk_bf16_f32 v146, v164, v165
	v_cvt_pk_bf16_f32 v147, v166, v167
	v_cvt_pk_bf16_f32 v148, v134, v135
	v_cvt_pk_bf16_f32 v149, v132, v133
	v_cvt_pk_bf16_f32 v164, v130, v131
	v_cvt_pk_bf16_f32 v165, v128, v129
	v_cvt_pk_bf16_f32 v166, v126, v127
	v_cvt_pk_bf16_f32 v167, v124, v125
	v_permlane32_swap_b32_e32 v137, v139
	v_permlane32_swap_b32_e32 v142, v144
	v_permlane32_swap_b32_e32 v143, v145
	v_permlane32_swap_b32_e32 v146, v148
	v_permlane32_swap_b32_e32 v147, v149
	v_permlane32_swap_b32_e32 v164, v166
	v_permlane32_swap_b32_e32 v165, v167
	v_lshl_add_u64 v[168:169], v[160:161], 0, s[82:83]
	v_add_co_u32_e32 v124, vcc, s94, v168
	v_lshl_add_u64 v[170:171], v[158:159], 0, s[82:83]
	s_nop 0
	v_addc_co_u32_e32 v125, vcc, 0, v169, vcc
	v_add_co_u32_e32 v128, vcc, s95, v168
	s_mov_b32 s0, 0x1868e000
	s_nop 0
	v_addc_co_u32_e32 v129, vcc, 0, v169, vcc
	v_add_co_u32_e32 v132, vcc, s0, v170
	global_load_dwordx4 v[124:127], v[124:125], off
	s_nop 0
	global_load_dwordx4 v[128:131], v[128:129], off
	v_addc_co_u32_e32 v133, vcc, 0, v171, vcc
	global_load_dwordx4 v[132:135], v[132:133], off
	s_waitcnt lgkmcnt(0)
; #define SBAR() __builtin_amdgcn_sched_barrier(0)
; DEV void partialSM(f32x16& p0, f32x16& p1, float& m_reg, float& mn, float& alpha) {
;   constexpr float C = AT_SCALE * 1.4426950408889634f;
;   float pmax = p0[0];
; #pragma unroll
;   for (int r = 1; r < 16; ++r) pmax = fmaxf(pmax, p0[r]);
; #pragma unroll
;   for (int r = 0; r < 16; ++r) pmax = fmaxf(pmax, p1[r]);
;   { auto rr = __builtin_amdgcn_permlane32_swap(__float_as_uint(pmax), __float_as_uint(pmax), false, false);
;     pmax = fmaxf(__uint_as_float(rr[0]), __uint_as_float(rr[1])); }
;   if (__builtin_expect(__all(pmax - m_reg <= AT_THR / AT_SCALE), 1)) { mn = m_reg; alpha = 1.f; }
;   else { mn = fmaxf(m_reg, pmax); alpha = __builtin_amdgcn_exp2f((m_reg - mn) * C); m_reg = mn; }
; template <int D0> DEV void pv_one(f32x16& od, int vb, bf16x8 pa0, bf16x8 pa1, bf16x8 pa2, bf16x8 pa3) {
;   const s16x4 l0 = tr_read<v_rd_off(D0, 0, 0)>(vb), h0 = tr_read<v_rd_off(D0, 0, 1)>(vb), l1 = tr_read<v_rd_off(D0, 1, 0)>(vb), h1 = tr_read<v_rd_off(D0, 1, 1)>(vb);
;   const s16x4 l2 = tr_read<v_rd_off(D0, 2, 0)>(vb), h2 = tr_read<v_rd_off(D0, 2, 1)>(vb), l3 = tr_read<v_rd_off(D0, 3, 0)>(vb), h3 = tr_read<v_rd_off(D0, 3, 1)>(vb);
;   asm volatile("s_waitcnt lgkmcnt(0)" ::: "memory"); SBAR();
;     ...
;   od = __builtin_amdgcn_mfma_f32_32x32x16_bf16(pa0, PK(l0, h0), od, 0, 0, 0);
;   od = __builtin_amdgcn_mfma_f32_32x32x16_bf16(pa1, PK(l1, h1), od, 0, 0, 0);
;   od = __builtin_amdgcn_mfma_f32_32x32x16_bf16(pa2, PK(l2, h2), od, 0, 0, 0);
;   od = __builtin_amdgcn_mfma_f32_32x32x16_bf16(pa3, PK(l3, h3), od, 0, 0, 0);
;     ...
; }
; DEV void pv_d0(f32x16* o, int vb, bf16x8 pa0, bf16x8 pa1, bf16x8 pa2, bf16x8 pa3) {
;   pv_one<0>(o[0], vb, pa0, pa1, pa2, pa3); pv_one<1>(o[1], vb, pa0, pa1, pa2, pa3); pv_one<2>(o[2], vb, pa0, pa1, pa2, pa3); pv_one<3>(o[3], vb, pa0, pa1, pa2, pa3);
	s_nop 0
	v_mfma_f32_32x32x16_bf16 v[0:15], v[136:139], v[186:189], v[0:15]
	ds_read_b64_tr_b16 v[186:187], v219 offset:0x200
	ds_read_b64_tr_b16 v[188:189], v219 offset:0xa00
	v_mfma_f32_32x32x16_bf16 v[0:15], v[142:145], v[190:193], v[0:15]
	ds_read_b64_tr_b16 v[190:191], v219 offset:0x1200
	ds_read_b64_tr_b16 v[192:193], v219 offset:0x1a00
	v_mfma_f32_32x32x16_bf16 v[0:15], v[146:149], v[222:225], v[0:15]
	ds_read_b64_tr_b16 v[222:223], v219 offset:0x2200
	ds_read_b64_tr_b16 v[224:225], v219 offset:0x2a00
	v_mfma_f32_32x32x16_bf16 v[0:15], v[164:167], v[226:229], v[0:15]
	ds_read_b64_tr_b16 v[226:227], v219 offset:0x3200
	ds_read_b64_tr_b16 v[228:229], v219 offset:0x3a00
	s_waitcnt lgkmcnt(0)
	v_mfma_f32_32x32x16_bf16 v[48:63], v[136:139], v[186:189], v[48:63]
	ds_read_b64_tr_b16 v[186:187], v219 offset:0x400
	ds_read_b64_tr_b16 v[188:189], v219 offset:0xc00
	v_mfma_f32_32x32x16_bf16 v[48:63], v[142:145], v[190:193], v[48:63]
	ds_read_b64_tr_b16 v[190:191], v219 offset:0x1400
	ds_read_b64_tr_b16 v[192:193], v219 offset:0x1c00
	v_mfma_f32_32x32x16_bf16 v[48:63], v[146:149], v[222:225], v[48:63]
	ds_read_b64_tr_b16 v[222:223], v219 offset:0x2400
	ds_read_b64_tr_b16 v[224:225], v219 offset:0x2c00
	v_mfma_f32_32x32x16_bf16 v[48:63], v[164:167], v[226:229], v[48:63]
	ds_read_b64_tr_b16 v[226:227], v219 offset:0x3400
	ds_read_b64_tr_b16 v[228:229], v219 offset:0x3c00
	s_waitcnt lgkmcnt(0)
	v_mfma_f32_32x32x16_bf16 v[32:47], v[136:139], v[186:189], v[32:47]
	ds_read_b64_tr_b16 v[186:187], v219 offset:0x600
	ds_read_b64_tr_b16 v[188:189], v219 offset:0xe00
	v_mfma_f32_32x32x16_bf16 v[32:47], v[142:145], v[190:193], v[32:47]
	ds_read_b64_tr_b16 v[190:191], v219 offset:0x1600
	ds_read_b64_tr_b16 v[192:193], v219 offset:0x1e00
	v_mfma_f32_32x32x16_bf16 v[32:47], v[146:149], v[222:225], v[32:47]
	ds_read_b64_tr_b16 v[222:223], v219 offset:0x2600
	ds_read_b64_tr_b16 v[224:225], v219 offset:0x2e00
	v_mfma_f32_32x32x16_bf16 v[32:47], v[164:167], v[226:229], v[32:47]
	ds_read_b64_tr_b16 v[226:227], v219 offset:0x3600
	ds_read_b64_tr_b16 v[228:229], v219 offset:0x3e00
	s_waitcnt lgkmcnt(0)
	v_mfma_f32_32x32x16_bf16 v[16:31], v[136:139], v[186:189], v[16:31]
	v_max_f32_e32 v136, v80, v81
	v_max3_f32 v136, v136, v82, v83
	v_max3_f32 v136, v136, v84, v85
	v_max3_f32 v136, v136, v86, v87
	v_max3_f32 v136, v136, v88, v89
	v_max3_f32 v136, v136, v90, v91
	v_max3_f32 v136, v136, v92, v93
	v_max3_f32 v136, v136, v94, v95
	v_mfma_f32_32x32x16_bf16 v[16:31], v[142:145], v[190:193], v[16:31]
	v_max3_f32 v136, v136, v64, v65
	v_max3_f32 v136, v136, v66, v67
	v_max3_f32 v136, v136, v68, v69
	v_max3_f32 v136, v136, v70, v71
	v_max3_f32 v136, v136, v72, v73
	v_max3_f32 v136, v136, v74, v75
	v_max3_f32 v136, v136, v76, v77
	v_max3_f32 v136, v136, v78, v79
	v_mfma_f32_32x32x16_bf16 v[16:31], v[146:149], v[222:225], v[16:31]
	v_mov_b32_e32 v137, v136
	s_nop 1
	v_permlane32_swap_b32_e32 v136, v137
	v_max_f32_e32 v136, v136, v137
	v_cmp_ge_f32_e32 vcc, s18, v136
	v_mfma_f32_32x32x16_bf16 v[16:31], v[164:167], v[226:229], v[16:31]
	s_cmp_eq_u64 vcc, exec
	s_cselect_b64 s[0:1], -1, 0
	s_cbranch_scc1 .Lattn_fast3
	v_max_f32_e32 v136, 0, v136
	v_exp_f32_e64 v137, -v136
